# attention K/V prefetch tile index clamped to the last valid tile in two of the four unrolled slots (less over-read past each q-block)
# baseline (speedup 1.0000x reference)
; __device__ __forceinline__ void attn_tile(int t, int buf, LAS unsigned char* lds, const bf16x8 (&qr)[4], float cq2, int qlo, int qpos, int q32, int hi,
;                                           float& mrun, float& lrun, f32x16& o0, f32x16& o1) {
;     const LAS float* c2s = (const LAS float*)(lds + AT_C2);
;     const LAS unsigned char* Kt = lds + AT_K + buf * AT_KB; const LAS unsigned char* Vt = lds + AT_VT + buf * AT_VB;
;     f32x16 s0, s1;
; #pragma unroll
;     for (int j = 0; j < 4; ++j) {
;         const f32x4 c0 = *(const LAS f32x4*)(c2s + 64 * t + 8 * j + 4 * hi), c1 = *(const LAS f32x4*)(c2s + 64 * t + 32 + 8 * j + 4 * hi);
; #pragma unroll
;         for (int e = 0; e < 4; ++e) { s0[4 * j + e] = c0[e]; s1[4 * j + e] = c1[e]; }
;     }
; #pragma unroll
;     for (int d0 = 0; d0 < 4; ++d0) {
;         const bf16x8 k0 = *(const LAS bf16x8*)(Kt + q32 * 144 + d0 * 32 + hi * 16);
;         const bf16x8 k1 = *(const LAS bf16x8*)(Kt + (32 + q32) * 144 + d0 * 32 + hi * 16);
;         s0 = __builtin_amdgcn_mfma_f32_32x32x16_bf16(k0, qr[d0], s0, 0, 0, 0);
;         s1 = __builtin_amdgcn_mfma_f32_32x32x16_bf16(k1, qr[d0], s1, 0, 0, 0);
;     }
;     if (64 * t + 63 > qlo) {
; #pragma unroll
;         for (int r = 0; r < 16; ++r) { const int kv = 64 * t + crow(r, hi); if (kv > qpos) s0[r] = -INFINITY; if (kv + 32 > qpos) s1[r] = -INFINITY; }
;     }
;     float mx = fmaxf(s0[0], s1[0]);
; #pragma unroll
;     for (int r = 1; r < 16; ++r) mx = fmaxf(mx, fmaxf(s0[r], s1[r]));
;     mx = fmaxf(mx, __shfl_xor(mx, 32));
;     const float mnew = fmaxf(mrun, mx);
;     if (__any(mnew > mrun)) {
;         const float alpha = fexp2(mrun - mnew); lrun *= alpha;
; #pragma unroll
;         for (int r = 0; r < 16; ++r) { o0[r] *= alpha; o1[r] *= alpha; }
;     }
;     mrun = mnew;
;     f32x2 ls2 = (f32x2){0.f, 0.f};
; #pragma unroll
;     for (int r = 0; r < 16; r += 2) {
;         const f32x2 d0 = (f32x2){s0[r], s0[r + 1]} - mnew, d1 = (f32x2){s1[r], s1[r + 1]} - mnew;
;         f32x2 e0, e1; e0.x = fexp2(d0.x); e0.y = fexp2(d0.y); e1.x = fexp2(d1.x); e1.y = fexp2(d1.y);
;         s0[r] = e0.x; s0[r + 1] = e0.y; s1[r] = e1.x; s1[r + 1] = e1.y;
;         ls2 += e0 + e1;
;     }
;     lrun += ls2.x + ls2.y;
; #pragma unroll
;     for (int p = 0; p < 2; ++p)
; #pragma unroll
;         for (int sx = 0; sx < 2; ++sx) {
;             u32x4 pw;
.LnoV_E:
	s_waitcnt lgkmcnt(0)
	s_barrier
	s_add_i32 s6, s22, 2
	s_add_i32 s7, s20, -1
	s_min_u32 s6, s6, s7
	s_lshl_b32 s6, s6, 18
	s_add_u32 s98, s8, s6
	s_addc_u32 s99, s9, 0
	global_load_dwordx4 v[82:85], v158, s[98:99] offset:1024
	s_add_i32 s6, s22, 1
	s_min_u32 s6, s6, s7
	s_lshl_b32 s6, s6, 18
	s_add_u32 s100, s8, s6
	s_addc_u32 s101, s9, 0
	global_load_dwordx4 v[94:97], v158, s[100:101] offset:2048
	s_lshl_b32 s6, s22, 6
	s_cmp_le_i32 s6, s23
	s_cbranch_scc0 .Lnoproc_E
	ds_read_b128 v[124:127], v112 offset:8448
	ds_read_b128 v[34:37], v111
	ds_read_b128 v[38:41], v111 offset:32
	ds_read_b128 v[42:45], v111 offset:64
	ds_read_b128 v[46:49], v111 offset:96
	ds_read_b128 v[128:131], v112 offset:13056
	ds_read_b128 v[50:53], v111 offset:128
	ds_read_b128 v[54:57], v111 offset:160
	ds_read_b128 v[58:61], v111 offset:192
	ds_read_b128 v[62:65], v111 offset:224
	ds_read_b128 v[132:135], v112 offset:8480
	ds_read_b128 v[136:139], v112 offset:13088
	ds_read_b128 v[140:143], v112 offset:8512
	ds_read_b128 v[144:147], v112 offset:13120
	s_cmp_eq_u32 s27, 0
	s_cbranch_scc1 .Lqkonly_E
	v_sub_f32_e32 v206, v206, v114
	v_sub_f32_e32 v207, v207, v114
	v_sub_f32_e32 v208, v208, v114
	v_sub_f32_e32 v209, v209, v114
	v_sub_f32_e32 v210, v210, v114
	v_sub_f32_e32 v211, v211, v114
	v_sub_f32_e32 v212, v212, v114
	v_sub_f32_e32 v213, v213, v114
	v_exp_f32_e32 v206, v206
	v_exp_f32_e32 v207, v207
	v_exp_f32_e32 v208, v208
	v_exp_f32_e32 v209, v209
	v_exp_f32_e32 v210, v210
	v_exp_f32_e32 v211, v211
	v_exp_f32_e32 v212, v212
	v_exp_f32_e32 v213, v213
	v_cvt_pk_bf16_f32 v118, v206, v207
	v_cvt_pk_bf16_f32 v119, v208, v209
	v_cvt_pk_bf16_f32 v120, v210, v211
	v_cvt_pk_bf16_f32 v121, v212, v213
	v_add_f32_e32 v116, v206, v208
	v_add_f32_e32 v117, v207, v209
	v_add_f32_e32 v116, v116, v210
	v_add_f32_e32 v117, v117, v211
	v_add_f32_e32 v116, v116, v212
	v_add_f32_e32 v117, v117, v213
	s_waitcnt lgkmcnt(9)
	v_mfma_f32_32x32x16_bf16 v[34:49], v[124:127], v[78:81], v[34:49]
	ds_read_b128 v[148:151], v112 offset:8544
	ds_read_b128 v[152:155], v112 offset:13152
	s_waitcnt lgkmcnt(6)
	v_mfma_f32_32x32x16_bf16 v[50:65], v[128:131], v[78:81], v[50:65]
	s_waitcnt lgkmcnt(5)
	v_mfma_f32_32x32x16_bf16 v[34:49], v[132:135], v[74:77], v[34:49]
	s_waitcnt lgkmcnt(4)
	v_mfma_f32_32x32x16_bf16 v[50:65], v[136:139], v[74:77], v[50:65]
	s_waitcnt lgkmcnt(3)
	v_mfma_f32_32x32x16_bf16 v[34:49], v[140:143], v[70:73], v[34:49]
	s_waitcnt lgkmcnt(2)
	v_mfma_f32_32x32x16_bf16 v[50:65], v[144:147], v[70:73], v[50:65]
	s_waitcnt lgkmcnt(1)
	v_mfma_f32_32x32x16_bf16 v[34:49], v[148:151], v[66:69], v[34:49]
	s_waitcnt lgkmcnt(0)
	v_mfma_f32_32x32x16_bf16 v[50:65], v[152:155], v[66:69], v[50:65]
	v_add_u32_e32 v122, 0x8800, v113
	v_add_u32_e32 v123, 0x9800, v113
	ds_read2_b64 v[166:169], v122 offset0:96 offset1:98
	ds_read2_b64 v[170:173], v123 offset0:128 offset1:130
	ds_read2_b64 v[174:177], v122 offset0:100 offset1:102
	ds_read2_b64 v[178:181], v123 offset0:132 offset1:134
	ds_read2_b64 v[182:185], v122 offset0:104 offset1:106
	ds_read2_b64 v[186:189], v123 offset0:136 offset1:138
	ds_read2_b64 v[190:193], v122 offset0:108 offset1:110
	ds_read2_b64 v[194:197], v123 offset0:140 offset1:142
	v_sub_f32_e32 v214, v214, v114
	v_sub_f32_e32 v215, v215, v114
	v_sub_f32_e32 v216, v216, v114
	v_sub_f32_e32 v217, v217, v114
	v_sub_f32_e32 v218, v218, v114
	v_sub_f32_e32 v219, v219, v114
	v_sub_f32_e32 v220, v220, v114
	v_sub_f32_e32 v221, v221, v114
	v_exp_f32_e32 v214, v214
	v_exp_f32_e32 v215, v215
	v_exp_f32_e32 v216, v216
	v_exp_f32_e32 v217, v217
	v_exp_f32_e32 v218, v218
	v_exp_f32_e32 v219, v219
	v_exp_f32_e32 v220, v220
	v_exp_f32_e32 v221, v221
	s_waitcnt lgkmcnt(0)
	v_mfma_f32_32x32x16_bf16 v[18:33], v[166:169], v[118:121], v[18:33]
	v_mfma_f32_32x32x16_bf16 v[2:17], v[170:173], v[118:121], v[2:17]
	v_cvt_pk_bf16_f32 v118, v214, v215
	v_cvt_pk_bf16_f32 v119, v216, v217
	v_cvt_pk_bf16_f32 v120, v218, v219
	v_cvt_pk_bf16_f32 v121, v220, v221
	v_add_f32_e32 v116, v116, v214
	v_add_f32_e32 v117, v117, v215
	v_add_f32_e32 v116, v116, v216
	v_add_f32_e32 v117, v117, v217
	v_add_f32_e32 v116, v116, v218
	v_add_f32_e32 v117, v117, v219
	v_add_f32_e32 v116, v116, v220
	v_add_f32_e32 v117, v117, v221
	v_mfma_f32_32x32x16_bf16 v[18:33], v[174:177], v[118:121], v[18:33]
	v_mfma_f32_32x32x16_bf16 v[2:17], v[178:181], v[118:121], v[2:17]
	v_sub_f32_e32 v222, v222, v114
	v_sub_f32_e32 v223, v223, v114
	v_sub_f32_e32 v224, v224, v114
	v_sub_f32_e32 v225, v225, v114
	v_sub_f32_e32 v226, v226, v114
	v_sub_f32_e32 v227, v227, v114
	v_sub_f32_e32 v228, v228, v114
	v_sub_f32_e32 v229, v229, v114
	v_exp_f32_e32 v222, v222
	v_exp_f32_e32 v223, v223
	v_exp_f32_e32 v224, v224
	v_exp_f32_e32 v225, v225
	v_exp_f32_e32 v226, v226
	v_exp_f32_e32 v227, v227
	v_exp_f32_e32 v228, v228
	v_exp_f32_e32 v229, v229
	v_cvt_pk_bf16_f32 v118, v222, v223
	v_cvt_pk_bf16_f32 v119, v224, v225
	v_cvt_pk_bf16_f32 v120, v226, v227
	v_cvt_pk_bf16_f32 v121, v228, v229
	v_add_f32_e32 v116, v116, v222
	v_add_f32_e32 v117, v117, v223
	v_add_f32_e32 v116, v116, v224
	v_add_f32_e32 v117, v117, v225
	v_add_f32_e32 v116, v116, v226
	v_add_f32_e32 v117, v117, v227
	v_add_f32_e32 v116, v116, v228
	v_add_f32_e32 v117, v117, v229
	v_mfma_f32_32x32x16_bf16 v[18:33], v[182:185], v[118:121], v[18:33]
	v_mfma_f32_32x32x16_bf16 v[2:17], v[186:189], v[118:121], v[2:17]
	v_sub_f32_e32 v230, v230, v114
	v_sub_f32_e32 v231, v231, v114
	v_sub_f32_e32 v232, v232, v114
	v_sub_f32_e32 v233, v233, v114
	v_sub_f32_e32 v234, v234, v114
	v_sub_f32_e32 v235, v235, v114
	v_sub_f32_e32 v236, v236, v114
	v_sub_f32_e32 v237, v237, v114
	v_exp_f32_e32 v230, v230
	v_exp_f32_e32 v231, v231
	v_exp_f32_e32 v232, v232
	v_exp_f32_e32 v233, v233
	v_exp_f32_e32 v234, v234
	v_exp_f32_e32 v235, v235
	v_exp_f32_e32 v236, v236
	v_exp_f32_e32 v237, v237
	v_cvt_pk_bf16_f32 v118, v230, v231
	v_cvt_pk_bf16_f32 v119, v232, v233
	v_cvt_pk_bf16_f32 v120, v234, v235
	v_cvt_pk_bf16_f32 v121, v236, v237
	v_add_f32_e32 v116, v116, v230
	v_add_f32_e32 v117, v117, v231
	v_add_f32_e32 v116, v116, v232
	v_add_f32_e32 v117, v117, v233
	v_add_f32_e32 v116, v116, v234
	v_add_f32_e32 v117, v117, v235
	v_add_f32_e32 v116, v116, v236
	v_add_f32_e32 v117, v117, v237
	v_mfma_f32_32x32x16_bf16 v[18:33], v[190:193], v[118:121], v[18:33]
	v_mfma_f32_32x32x16_bf16 v[2:17], v[194:197], v[118:121], v[2:17]
	v_add_f32_e32 v116, v116, v117
	v_add_f32_e32 v109, v109, v116
	s_branch .Lmax_E

; __device__ __forceinline__ void attn_tile(int t, int buf, LAS unsigned char* lds, const bf16x8 (&qr)[4], float cq2, int qlo, int qpos, int q32, int hi,
;                                           float& mrun, float& lrun, f32x16& o0, f32x16& o1) {
;     const LAS float* c2s = (const LAS float*)(lds + AT_C2);
;     const LAS unsigned char* Kt = lds + AT_K + buf * AT_KB; const LAS unsigned char* Vt = lds + AT_VT + buf * AT_VB;
;     f32x16 s0, s1;
; #pragma unroll
;     for (int j = 0; j < 4; ++j) {
;         const f32x4 c0 = *(const LAS f32x4*)(c2s + 64 * t + 8 * j + 4 * hi), c1 = *(const LAS f32x4*)(c2s + 64 * t + 32 + 8 * j + 4 * hi);
; #pragma unroll
;         for (int e = 0; e < 4; ++e) { s0[4 * j + e] = c0[e]; s1[4 * j + e] = c1[e]; }
;     }
; #pragma unroll
;     for (int d0 = 0; d0 < 4; ++d0) {
;         const bf16x8 k0 = *(const LAS bf16x8*)(Kt + q32 * 144 + d0 * 32 + hi * 16);
;         const bf16x8 k1 = *(const LAS bf16x8*)(Kt + (32 + q32) * 144 + d0 * 32 + hi * 16);
;         s0 = __builtin_amdgcn_mfma_f32_32x32x16_bf16(k0, qr[d0], s0, 0, 0, 0);
;         s1 = __builtin_amdgcn_mfma_f32_32x32x16_bf16(k1, qr[d0], s1, 0, 0, 0);
;     }
;     if (64 * t + 63 > qlo) {
; #pragma unroll
;         for (int r = 0; r < 16; ++r) { const int kv = 64 * t + crow(r, hi); if (kv > qpos) s0[r] = -INFINITY; if (kv + 32 > qpos) s1[r] = -INFINITY; }
;     }
;     float mx = fmaxf(s0[0], s1[0]);
; #pragma unroll
;     for (int r = 1; r < 16; ++r) mx = fmaxf(mx, fmaxf(s0[r], s1[r]));
;     mx = fmaxf(mx, __shfl_xor(mx, 32));
;     const float mnew = fmaxf(mrun, mx);
;     if (__any(mnew > mrun)) {
;         const float alpha = fexp2(mrun - mnew); lrun *= alpha;
; #pragma unroll
;         for (int r = 0; r < 16; ++r) { o0[r] *= alpha; o1[r] *= alpha; }
;     }
;     mrun = mnew;
;     f32x2 ls2 = (f32x2){0.f, 0.f};
; #pragma unroll
;     for (int r = 0; r < 16; r += 2) {
;         const f32x2 d0 = (f32x2){s0[r], s0[r + 1]} - mnew, d1 = (f32x2){s1[r], s1[r + 1]} - mnew;
;         f32x2 e0, e1; e0.x = fexp2(d0.x); e0.y = fexp2(d0.y); e1.x = fexp2(d1.x); e1.y = fexp2(d1.y);
;         s0[r] = e0.x; s0[r + 1] = e0.y; s1[r] = e1.x; s1[r + 1] = e1.y;
;         ls2 += e0 + e1;
;     }
;     lrun += ls2.x + ls2.y;
; #pragma unroll
;     for (int p = 0; p < 2; ++p)
; #pragma unroll
;         for (int sx = 0; sx < 2; ++sx) {
;             u32x4 pw;
.Lend_E:
.Lslot_O:
	s_waitcnt vmcnt(2)
	ds_write_b128 v156, v[90:93] offset:17664
	ds_write_b16 v157, v86 offset:26880
	ds_write_b16_d16_hi v157, v86 offset:27016
	ds_write_b16 v157, v87 offset:27152
	ds_write_b16_d16_hi v157, v87 offset:27288
	ds_write_b16 v157, v88 offset:27424
	ds_write_b16_d16_hi v157, v88 offset:27560
	ds_write_b16 v157, v89 offset:27696
	ds_write_b16_d16_hi v157, v89 offset:27832
	s_waitcnt lgkmcnt(0)
	s_barrier
	s_add_i32 s6, s22, 3
	s_add_i32 s7, s20, -1
	s_min_u32 s6, s6, s7
	s_lshl_b32 s6, s6, 18
	s_add_u32 s98, s8, s6
	s_addc_u32 s99, s9, 0
	global_load_dwordx4 v[90:93], v158, s[98:99] offset:1024
	s_add_i32 s6, s22, 2
	s_min_u32 s6, s6, s7
	s_lshl_b32 s6, s6, 18
	s_add_u32 s100, s8, s6
	s_addc_u32 s101, s9, 0
	global_load_dwordx4 v[86:89], v158, s[100:101] offset:2048
	s_lshl_b32 s6, s22, 6
	s_add_i32 s6, s6, 64
	s_cmp_le_i32 s6, s23
	s_cbranch_scc0 .Lnoproc_O
	ds_read_b128 v[124:127], v112 offset:17664
	ds_read_b128 v[206:209], v111 offset:256
	ds_read_b128 v[210:213], v111 offset:288
	ds_read_b128 v[214:217], v111 offset:320
	ds_read_b128 v[218:221], v111 offset:352
	ds_read_b128 v[128:131], v112 offset:22272
	ds_read_b128 v[222:225], v111 offset:384
	ds_read_b128 v[226:229], v111 offset:416
	ds_read_b128 v[230:233], v111 offset:448
	ds_read_b128 v[234:237], v111 offset:480
	ds_read_b128 v[132:135], v112 offset:17696
	ds_read_b128 v[136:139], v112 offset:22304
	ds_read_b128 v[140:143], v112 offset:17728
	ds_read_b128 v[144:147], v112 offset:22336
	s_cmp_eq_u32 s26, 0
	s_cbranch_scc1 .Lqkonly_O
	v_sub_f32_e32 v34, v34, v114
	v_sub_f32_e32 v35, v35, v114
	v_sub_f32_e32 v36, v36, v114
	v_sub_f32_e32 v37, v37, v114
	v_sub_f32_e32 v38, v38, v114
	v_sub_f32_e32 v39, v39, v114
	v_sub_f32_e32 v40, v40, v114
	v_sub_f32_e32 v41, v41, v114
	v_exp_f32_e32 v34, v34
	v_exp_f32_e32 v35, v35
	v_exp_f32_e32 v36, v36
	v_exp_f32_e32 v37, v37
	v_exp_f32_e32 v38, v38
	v_exp_f32_e32 v39, v39
	v_exp_f32_e32 v40, v40
	v_exp_f32_e32 v41, v41
	v_cvt_pk_bf16_f32 v118, v34, v35
	v_cvt_pk_bf16_f32 v119, v36, v37
	v_cvt_pk_bf16_f32 v120, v38, v39
	v_cvt_pk_bf16_f32 v121, v40, v41
	v_add_f32_e32 v116, v34, v36
	v_add_f32_e32 v117, v35, v37
	v_add_f32_e32 v116, v116, v38
	v_add_f32_e32 v117, v117, v39
	v_add_f32_e32 v116, v116, v40
	v_add_f32_e32 v117, v117, v41
	s_waitcnt lgkmcnt(9)
	v_mfma_f32_32x32x16_bf16 v[206:221], v[124:127], v[78:81], v[206:221]
	ds_read_b128 v[148:151], v112 offset:17760
	ds_read_b128 v[152:155], v112 offset:22368
	s_waitcnt lgkmcnt(6)
	v_mfma_f32_32x32x16_bf16 v[222:237], v[128:131], v[78:81], v[222:237]
	s_waitcnt lgkmcnt(5)
	v_mfma_f32_32x32x16_bf16 v[206:221], v[132:135], v[74:77], v[206:221]
	s_waitcnt lgkmcnt(4)
	v_mfma_f32_32x32x16_bf16 v[222:237], v[136:139], v[74:77], v[222:237]
	s_waitcnt lgkmcnt(3)
	v_mfma_f32_32x32x16_bf16 v[206:221], v[140:143], v[70:73], v[206:221]
	s_waitcnt lgkmcnt(2)
	v_mfma_f32_32x32x16_bf16 v[222:237], v[144:147], v[70:73], v[222:237]
	s_waitcnt lgkmcnt(1)
	v_mfma_f32_32x32x16_bf16 v[206:221], v[148:151], v[66:69], v[206:221]
	s_waitcnt lgkmcnt(0)
	v_mfma_f32_32x32x16_bf16 v[222:237], v[152:155], v[66:69], v[222:237]
	v_add_u32_e32 v122, 0x6800, v113
	v_add_u32_e32 v123, 0x7800, v113
	ds_read2_b64 v[166:169], v122 offset0:32 offset1:34
	ds_read2_b64 v[170:173], v123 offset0:64 offset1:66
	ds_read2_b64 v[174:177], v122 offset0:36 offset1:38
	ds_read2_b64 v[178:181], v123 offset0:68 offset1:70
	ds_read2_b64 v[182:185], v122 offset0:40 offset1:42
	ds_read2_b64 v[186:189], v123 offset0:72 offset1:74
	ds_read2_b64 v[190:193], v122 offset0:44 offset1:46
	ds_read2_b64 v[194:197], v123 offset0:76 offset1:78
	v_sub_f32_e32 v42, v42, v114
	v_sub_f32_e32 v43, v43, v114
	v_sub_f32_e32 v44, v44, v114
	v_sub_f32_e32 v45, v45, v114
	v_sub_f32_e32 v46, v46, v114
	v_sub_f32_e32 v47, v47, v114
	v_sub_f32_e32 v48, v48, v114
	v_sub_f32_e32 v49, v49, v114
	v_exp_f32_e32 v42, v42
	v_exp_f32_e32 v43, v43
	v_exp_f32_e32 v44, v44
	v_exp_f32_e32 v45, v45
	v_exp_f32_e32 v46, v46
	v_exp_f32_e32 v47, v47
	v_exp_f32_e32 v48, v48
	v_exp_f32_e32 v49, v49
	s_waitcnt lgkmcnt(0)
	v_mfma_f32_32x32x16_bf16 v[18:33], v[166:169], v[118:121], v[18:33]
	v_mfma_f32_32x32x16_bf16 v[2:17], v[170:173], v[118:121], v[2:17]
	v_cvt_pk_bf16_f32 v118, v42, v43
	v_cvt_pk_bf16_f32 v119, v44, v45
	v_cvt_pk_bf16_f32 v120, v46, v47
	v_cvt_pk_bf16_f32 v121, v48, v49
	v_add_f32_e32 v116, v116, v42
	v_add_f32_e32 v117, v117, v43
	v_add_f32_e32 v116, v116, v44
	v_add_f32_e32 v117, v117, v45
	v_add_f32_e32 v116, v116, v46
	v_add_f32_e32 v117, v117, v47
	v_add_f32_e32 v116, v116, v48
	v_add_f32_e32 v117, v117, v49
	v_mfma_f32_32x32x16_bf16 v[18:33], v[174:177], v[118:121], v[18:33]
	v_mfma_f32_32x32x16_bf16 v[2:17], v[178:181], v[118:121], v[2:17]
	v_sub_f32_e32 v50, v50, v114
	v_sub_f32_e32 v51, v51, v114
	v_sub_f32_e32 v52, v52, v114
	v_sub_f32_e32 v53, v53, v114
	v_sub_f32_e32 v54, v54, v114
	v_sub_f32_e32 v55, v55, v114
	v_sub_f32_e32 v56, v56, v114
	v_sub_f32_e32 v57, v57, v114
	v_exp_f32_e32 v50, v50
	v_exp_f32_e32 v51, v51
	v_exp_f32_e32 v52, v52
	v_exp_f32_e32 v53, v53
	v_exp_f32_e32 v54, v54
	v_exp_f32_e32 v55, v55
	v_exp_f32_e32 v56, v56
	v_exp_f32_e32 v57, v57
	v_cvt_pk_bf16_f32 v118, v50, v51
	v_cvt_pk_bf16_f32 v119, v52, v53
	v_cvt_pk_bf16_f32 v120, v54, v55
	v_cvt_pk_bf16_f32 v121, v56, v57
	v_add_f32_e32 v116, v116, v50
	v_add_f32_e32 v117, v117, v51
	v_add_f32_e32 v116, v116, v52
	v_add_f32_e32 v117, v117, v53
	v_add_f32_e32 v116, v116, v54
	v_add_f32_e32 v117, v117, v55
	v_add_f32_e32 v116, v116, v56
	v_add_f32_e32 v117, v117, v57
	v_mfma_f32_32x32x16_bf16 v[18:33], v[182:185], v[118:121], v[18:33]
	v_mfma_f32_32x32x16_bf16 v[2:17], v[186:189], v[118:121], v[2:17]
	v_sub_f32_e32 v58, v58, v114
	v_sub_f32_e32 v59, v59, v114
	v_sub_f32_e32 v60, v60, v114
	v_sub_f32_e32 v61, v61, v114
	v_sub_f32_e32 v62, v62, v114
	v_sub_f32_e32 v63, v63, v114
	v_sub_f32_e32 v64, v64, v114
	v_sub_f32_e32 v65, v65, v114
	v_exp_f32_e32 v58, v58
	v_exp_f32_e32 v59, v59
	v_exp_f32_e32 v60, v60
	v_exp_f32_e32 v61, v61
	v_exp_f32_e32 v62, v62
	v_exp_f32_e32 v63, v63
	v_exp_f32_e32 v64, v64
	v_exp_f32_e32 v65, v65
	v_cvt_pk_bf16_f32 v118, v58, v59
	v_cvt_pk_bf16_f32 v119, v60, v61
	v_cvt_pk_bf16_f32 v120, v62, v63
	v_cvt_pk_bf16_f32 v121, v64, v65
	v_add_f32_e32 v116, v116, v58
	v_add_f32_e32 v117, v117, v59
	v_add_f32_e32 v116, v116, v60
	v_add_f32_e32 v117, v117, v61
	v_add_f32_e32 v116, v116, v62
	v_add_f32_e32 v117, v117, v63
	v_add_f32_e32 v116, v116, v64
	v_add_f32_e32 v117, v117, v65
	v_mfma_f32_32x32x16_bf16 v[18:33], v[190:193], v[118:121], v[18:33]
	v_mfma_f32_32x32x16_bf16 v[2:17], v[194:197], v[118:121], v[2:17]
	v_add_f32_e32 v116, v116, v117
	v_add_f32_e32 v109, v109, v116
	s_branch .Lmax_O
